# DA latent loop softmax VALU packed: s-m via 8 v_pk_add_f32, row sum via 7 v_pk_add_f32 + 2 adds (was 16 sub + 17 add); f32 throughout
# baseline (speedup 1.0000x reference)
.Lmy_pp_nors_a:
	v_pk_add_f32 v[80:81], v[80:81], v[208:209] op_sel_hi:[1,0] neg_lo:[0,1] neg_hi:[0,1]
	v_exp_f32_e32 v80, v80
	v_mfma_f32_32x32x16_bf16 v[218:233], v[112:115], v[108:111], 0
	v_exp_f32_e32 v81, v81
	v_pk_add_f32 v[82:83], v[82:83], v[208:209] op_sel_hi:[1,0] neg_lo:[0,1] neg_hi:[0,1]
	v_exp_f32_e32 v82, v82
	v_exp_f32_e32 v83, v83
	v_pk_add_f32 v[84:85], v[84:85], v[208:209] op_sel_hi:[1,0] neg_lo:[0,1] neg_hi:[0,1]
	v_mfma_f32_32x32x16_bf16 v[218:233], v[10:13], v[104:107], v[218:233]
	v_exp_f32_e32 v84, v84
	v_pk_add_f32 v[86:87], v[86:87], v[208:209] op_sel_hi:[1,0] neg_lo:[0,1] neg_hi:[0,1]
	v_exp_f32_e32 v85, v85
	global_load_lds_dwordx4 v[242:243], off
	global_load_lds_dwordx4 v[242:243], off offset:1024
	v_mfma_f32_32x32x16_bf16 v[218:233], v[6:9], v[100:103], v[218:233]
	v_exp_f32_e32 v86, v86
	v_exp_f32_e32 v87, v87
	v_and_b32_e32 v244, s28, v244
	v_mfma_f32_32x32x16_bf16 v[218:233], v[2:5], v[96:99], v[218:233]
	v_pk_add_f32 v[88:89], v[88:89], v[208:209] op_sel_hi:[1,0] neg_lo:[0,1] neg_hi:[0,1]
	v_lshl_add_u64 v[242:243], v[244:245], 0, v[242:243]
	s_or_b32 s24, s24, 0x10000
	s_cmp_eq_u32 s13, 69
	s_cbranch_scc0 .Lmy_pp_nsw_a
	s_cmp_lg_u32 s29, 0
	s_cbranch_scc1 .Lmy_pp_nsw_a
	v_mov_b32_e32 v242, v250
	v_mov_b32_e32 v243, v251
.Lmy_pp_nsw_a:
	ds_read_b128 v[112:115], v249
	ds_read_b128 v[10:13], v249 offset:1024
	ds_read_b128 v[6:9], v249 offset:2048
	ds_read_b128 v[2:5], v249 offset:3072
	s_add_i32 s25, s25, 0x4000
	s_and_b32 s25, s25, 0xc000
	v_pk_add_f32 v[14:15], v[80:81], v[82:83]
	v_pk_add_f32 v[14:15], v[14:15], v[84:85]
	v_pk_add_f32 v[14:15], v[14:15], v[86:87]
	v_cvt_pk_bf16_f32 v80, v80, v81
	v_cvt_pk_bf16_f32 v81, v82, v83
	v_cvt_pk_bf16_f32 v82, v84, v85
	v_cvt_pk_bf16_f32 v83, v86, v87
	v_pk_add_f32 v[90:91], v[90:91], v[208:209] op_sel_hi:[1,0] neg_lo:[0,1] neg_hi:[0,1]
	v_pk_add_f32 v[92:93], v[92:93], v[208:209] op_sel_hi:[1,0] neg_lo:[0,1] neg_hi:[0,1]
	s_waitcnt lgkmcnt(4)
	v_mfma_f32_32x32x16_bf16 v[64:79], v[144:147], v[80:83], v[64:79]
	v_pk_add_f32 v[94:95], v[94:95], v[208:209] op_sel_hi:[1,0] neg_lo:[0,1] neg_hi:[0,1]
	v_exp_f32_e32 v88, v88
	v_exp_f32_e32 v89, v89
	v_mfma_f32_32x32x16_bf16 v[48:63], v[136:139], v[80:83], v[48:63]
	v_exp_f32_e32 v90, v90
	v_exp_f32_e32 v91, v91
	v_exp_f32_e32 v92, v92
	v_mfma_f32_32x32x16_bf16 v[32:47], v[132:135], v[80:83], v[32:47]
	v_exp_f32_e32 v93, v93
	v_exp_f32_e32 v94, v94
	v_exp_f32_e32 v95, v95
	v_mfma_f32_32x32x16_bf16 v[16:31], v[116:119], v[80:83], v[16:31]
	s_cmp_eq_u32 s29, 0
	s_cbranch_scc1 .Lmy_pp_nbm_a
	s_waitcnt vmcnt(4) lgkmcnt(0)
	s_barrier
.Lmy_pp_nbm_a:
	v_pk_add_f32 v[14:15], v[14:15], v[88:89]
	v_cvt_pk_bf16_f32 v84, v88, v89
	v_cvt_pk_bf16_f32 v85, v90, v91
	v_pk_add_f32 v[14:15], v[14:15], v[90:91]
	v_pk_add_f32 v[14:15], v[14:15], v[92:93]
	v_cvt_pk_bf16_f32 v86, v92, v93
	v_cvt_pk_bf16_f32 v87, v94, v95
	v_pk_add_f32 v[14:15], v[14:15], v[94:95]
	s_add_i32 s13, s13, -1
	v_mfma_f32_32x32x16_bf16 v[64:79], v[128:131], v[84:87], v[64:79]
	v_add_f32_e32 v14, v14, v15
	v_mfma_f32_32x32x16_bf16 v[48:63], v[140:143], v[84:87], v[48:63]
	v_add_f32_e32 v0, v0, v14
	v_mfma_f32_32x32x16_bf16 v[32:47], v[124:127], v[84:87], v[32:47]
	v_mfma_f32_32x32x16_bf16 v[16:31], v[120:123], v[84:87], v[16:31]
	s_cmp_lg_u32 s29, 0
	s_cbranch_scc1 .Lmy_pp_nbe_a
	s_waitcnt vmcnt(4) lgkmcnt(0)
	s_barrier

.Lmy_pp_nors_b:
	v_pk_add_f32 v[218:219], v[218:219], v[208:209] op_sel_hi:[1,0] neg_lo:[0,1] neg_hi:[0,1]
	v_exp_f32_e32 v218, v218
	v_mfma_f32_32x32x16_bf16 v[80:95], v[112:115], v[108:111], 0
	v_exp_f32_e32 v219, v219
	v_pk_add_f32 v[220:221], v[220:221], v[208:209] op_sel_hi:[1,0] neg_lo:[0,1] neg_hi:[0,1]
	v_exp_f32_e32 v220, v220
	v_exp_f32_e32 v221, v221
	v_pk_add_f32 v[222:223], v[222:223], v[208:209] op_sel_hi:[1,0] neg_lo:[0,1] neg_hi:[0,1]
	v_mfma_f32_32x32x16_bf16 v[80:95], v[10:13], v[104:107], v[80:95]
	v_exp_f32_e32 v222, v222
	v_pk_add_f32 v[224:225], v[224:225], v[208:209] op_sel_hi:[1,0] neg_lo:[0,1] neg_hi:[0,1]
	v_exp_f32_e32 v223, v223
	global_load_lds_dwordx4 v[242:243], off
	global_load_lds_dwordx4 v[242:243], off offset:1024
	v_mfma_f32_32x32x16_bf16 v[80:95], v[6:9], v[100:103], v[80:95]
	v_exp_f32_e32 v224, v224
	v_exp_f32_e32 v225, v225
	v_and_b32_e32 v244, s28, v244
	v_mfma_f32_32x32x16_bf16 v[80:95], v[2:5], v[96:99], v[80:95]
	v_pk_add_f32 v[226:227], v[226:227], v[208:209] op_sel_hi:[1,0] neg_lo:[0,1] neg_hi:[0,1]
	v_lshl_add_u64 v[242:243], v[244:245], 0, v[242:243]
	s_or_b32 s24, s24, 0x10000
	s_cmp_eq_u32 s13, 69
	s_cbranch_scc0 .Lmy_pp_nsw_b
	s_cmp_lg_u32 s29, 0
	s_cbranch_scc1 .Lmy_pp_nsw_b
	v_mov_b32_e32 v242, v250
	v_mov_b32_e32 v243, v251
.Lmy_pp_nsw_b:
	ds_read_b128 v[112:115], v249
	ds_read_b128 v[10:13], v249 offset:1024
	ds_read_b128 v[6:9], v249 offset:2048
	ds_read_b128 v[2:5], v249 offset:3072
	s_add_i32 s25, s25, 0x4000
	s_and_b32 s25, s25, 0xc000
	v_pk_add_f32 v[14:15], v[218:219], v[220:221]
	v_pk_add_f32 v[14:15], v[14:15], v[222:223]
	v_pk_add_f32 v[14:15], v[14:15], v[224:225]
	v_cvt_pk_bf16_f32 v218, v218, v219
	v_cvt_pk_bf16_f32 v219, v220, v221
	v_cvt_pk_bf16_f32 v220, v222, v223
	v_cvt_pk_bf16_f32 v221, v224, v225
	v_pk_add_f32 v[228:229], v[228:229], v[208:209] op_sel_hi:[1,0] neg_lo:[0,1] neg_hi:[0,1]
	v_pk_add_f32 v[230:231], v[230:231], v[208:209] op_sel_hi:[1,0] neg_lo:[0,1] neg_hi:[0,1]
	s_waitcnt lgkmcnt(4)
	v_mfma_f32_32x32x16_bf16 v[64:79], v[144:147], v[218:221], v[64:79]
	v_pk_add_f32 v[232:233], v[232:233], v[208:209] op_sel_hi:[1,0] neg_lo:[0,1] neg_hi:[0,1]
	v_exp_f32_e32 v226, v226
	v_exp_f32_e32 v227, v227
	v_mfma_f32_32x32x16_bf16 v[48:63], v[136:139], v[218:221], v[48:63]
	v_exp_f32_e32 v228, v228
	v_exp_f32_e32 v229, v229
	v_exp_f32_e32 v230, v230
	v_mfma_f32_32x32x16_bf16 v[32:47], v[132:135], v[218:221], v[32:47]
	v_exp_f32_e32 v231, v231
	v_exp_f32_e32 v232, v232
	v_exp_f32_e32 v233, v233
	v_mfma_f32_32x32x16_bf16 v[16:31], v[116:119], v[218:221], v[16:31]
	s_cmp_eq_u32 s29, 0
	s_cbranch_scc1 .Lmy_pp_nbm_b
	s_waitcnt vmcnt(4) lgkmcnt(0)
	s_barrier
.Lmy_pp_nbm_b:
	v_pk_add_f32 v[14:15], v[14:15], v[226:227]
	v_cvt_pk_bf16_f32 v222, v226, v227
	v_cvt_pk_bf16_f32 v223, v228, v229
	v_pk_add_f32 v[14:15], v[14:15], v[228:229]
	v_pk_add_f32 v[14:15], v[14:15], v[230:231]
	v_cvt_pk_bf16_f32 v224, v230, v231
	v_cvt_pk_bf16_f32 v225, v232, v233
	v_pk_add_f32 v[14:15], v[14:15], v[232:233]
	s_add_i32 s13, s13, -1
	v_mfma_f32_32x32x16_bf16 v[64:79], v[128:131], v[222:225], v[64:79]
	v_add_f32_e32 v14, v14, v15
	v_mfma_f32_32x32x16_bf16 v[48:63], v[140:143], v[222:225], v[48:63]
	v_add_f32_e32 v0, v0, v14
	v_mfma_f32_32x32x16_bf16 v[32:47], v[124:127], v[222:225], v[32:47]
	v_mfma_f32_32x32x16_bf16 v[16:31], v[120:123], v[222:225], v[16:31]
	s_cmp_lg_u32 s29, 0
	s_cbranch_scc1 .Lmy_pp_nbe_b
	s_waitcnt vmcnt(4) lgkmcnt(0)
	s_barrier

.Lmy_pp_nsw_t:
	s_add_i32 s25, s25, 0x4000
	s_and_b32 s25, s25, 0xc000
	v_pk_add_f32 v[14:15], v[80:81], v[82:83]
	v_pk_add_f32 v[14:15], v[14:15], v[84:85]
	v_pk_add_f32 v[14:15], v[14:15], v[86:87]
	v_cvt_pk_bf16_f32 v80, v80, v81
	v_cvt_pk_bf16_f32 v81, v82, v83
	v_cvt_pk_bf16_f32 v82, v84, v85
	v_cvt_pk_bf16_f32 v83, v86, v87
	v_pk_add_f32 v[90:91], v[90:91], v[208:209] op_sel_hi:[1,0] neg_lo:[0,1] neg_hi:[0,1]
	v_pk_add_f32 v[92:93], v[92:93], v[208:209] op_sel_hi:[1,0] neg_lo:[0,1] neg_hi:[0,1]
	s_waitcnt lgkmcnt(0)
	v_mfma_f32_32x32x16_bf16 v[64:79], v[144:147], v[80:83], v[64:79]
	v_pk_add_f32 v[94:95], v[94:95], v[208:209] op_sel_hi:[1,0] neg_lo:[0,1] neg_hi:[0,1]
	v_exp_f32_e32 v88, v88
	v_exp_f32_e32 v89, v89
	v_mfma_f32_32x32x16_bf16 v[48:63], v[136:139], v[80:83], v[48:63]
	v_exp_f32_e32 v90, v90
	v_exp_f32_e32 v91, v91
	v_exp_f32_e32 v92, v92
	v_mfma_f32_32x32x16_bf16 v[32:47], v[132:135], v[80:83], v[32:47]
	v_exp_f32_e32 v93, v93
	v_exp_f32_e32 v94, v94
	v_exp_f32_e32 v95, v95
	v_mfma_f32_32x32x16_bf16 v[16:31], v[116:119], v[80:83], v[16:31]
	s_cmp_eq_u32 s29, 0
	s_cbranch_scc1 .Lmy_pp_nbm_t
	s_waitcnt vmcnt(4) lgkmcnt(0)
	s_barrier

.Lmy_pp_nbe_t:
	s_setprio 0
	s_nop 0
	s_nop 0
	s_nop 0
